# speedup vs baseline: 1.0880x; 1.0002x over previous
; __device__ __forceinline__ void hgrn_phase(const Params& P, char* shm, int lbid) {
;     ...
;     f32x4 Sacc[8];
; #pragma unroll
;     for (int vt = 0; vt < 8; ++vt) Sacc[vt] = f32x4{0.f, 0.f, 0.f, 0.f};
;     char* sb = shm + SB0;
;     HG_ISSUE(0);
;     HG_PRODUCE(0);
;     HG_ISSUE(1);
;     for (int c = 0; c < NCH; ++c) {
.LBB0_907:
	s_or_b64 exec, exec, s[0:1]
	v_lshlrev_b32_e32 v107, 1, v15
	s_movk_i32 s0, 0x50
	v_mad_u32_u24 v4, v16, s0, v107
	v_readlane_b32 s0, v254, 7
	s_waitcnt vmcnt(0)
	ds_write_b16 v4, v0 offset:27648
	ds_write_b16_d16_hi v4, v0 offset:27728
	ds_write_b16 v4, v1 offset:27808
	ds_write_b16_d16_hi v4, v1 offset:27888
	ds_write_b16 v4, v2 offset:27968
	ds_write_b16_d16_hi v4, v2 offset:28048
	ds_write_b16 v4, v3 offset:28128
	ds_write_b16_d16_hi v4, v3 offset:28208
	v_add_u32_e32 v0, s0, v114
	v_mul_u32_u24_e32 v106, 0x50, v16
	v_ashrrev_i32_e32 v1, 31, v0
	v_add_u32_e32 v4, s0, v94
	v_add_u32_e32 v8, s0, v95
	v_add_u32_e32 v16, s0, v96
	v_lshlrev_b64 v[0:1], 9, v[0:1]
	v_ashrrev_i32_e32 v5, 31, v4
	v_ashrrev_i32_e32 v9, 31, v8
	s_waitcnt lgkmcnt(14)
	v_ashrrev_i32_e32 v17, 31, v16
	v_lshl_add_u64 v[0:1], v[0:1], 0, v[72:73]
	v_lshlrev_b64 v[4:5], 9, v[4:5]
	v_lshlrev_b64 v[8:9], 9, v[8:9]
	v_lshlrev_b64 v[16:17], 9, v[16:17]
	v_lshl_add_u64 v[2:3], v[0:1], 2, s[34:35]
	v_lshl_add_u64 v[0:1], v[0:1], 1, s[62:63]
	v_lshl_add_u64 v[4:5], v[4:5], 0, v[72:73]
	v_lshl_add_u64 v[8:9], v[8:9], 0, v[72:73]
	v_lshl_add_u64 v[16:17], v[16:17], 0, v[72:73]
	v_lshl_add_u64 v[6:7], v[4:5], 2, s[34:35]
	v_lshl_add_u64 v[4:5], v[4:5], 1, s[62:63]
	v_lshl_add_u64 v[10:11], v[8:9], 2, s[34:35]
	v_lshl_add_u64 v[8:9], v[8:9], 1, s[62:63]
	v_lshl_add_u64 v[18:19], v[16:17], 2, s[34:35]
	v_lshl_add_u64 v[16:17], v[16:17], 1, s[62:63]
	global_load_dword v84, v[2:3], off
	global_load_ushort v125, v[0:1], off
	global_load_dword v85, v[6:7], off
	global_load_ushort v124, v[4:5], off
	global_load_dword v78, v[10:11], off
	global_load_ushort v123, v[8:9], off
	global_load_dword v79, v[18:19], off
	global_load_ushort v121, v[16:17], off
	v_add_u32_e32 v0, s0, v97
	v_ashrrev_i32_e32 v1, 31, v0
	v_add_u32_e32 v4, s0, v99
	v_add_u32_e32 v8, s0, v101
	v_add_u32_e32 v16, s0, v103
	v_lshlrev_b64 v[0:1], 9, v[0:1]
	v_ashrrev_i32_e32 v5, 31, v4
	v_ashrrev_i32_e32 v9, 31, v8
	v_ashrrev_i32_e32 v17, 31, v16
	v_lshl_add_u64 v[0:1], v[0:1], 0, v[72:73]
	v_lshlrev_b64 v[4:5], 9, v[4:5]
	v_lshlrev_b64 v[8:9], 9, v[8:9]
	v_lshlrev_b64 v[16:17], 9, v[16:17]
	v_lshl_add_u64 v[2:3], v[0:1], 2, s[34:35]
	v_lshl_add_u64 v[4:5], v[4:5], 0, v[72:73]
	v_lshl_add_u64 v[8:9], v[8:9], 0, v[72:73]
	v_lshl_add_u64 v[16:17], v[16:17], 0, v[72:73]
	v_lshl_add_u64 v[0:1], v[0:1], 1, s[62:63]
	v_lshl_add_u64 v[6:7], v[4:5], 2, s[34:35]
	v_lshl_add_u64 v[4:5], v[4:5], 1, s[62:63]
	v_lshl_add_u64 v[10:11], v[8:9], 2, s[34:35]
	v_lshl_add_u64 v[8:9], v[8:9], 1, s[62:63]
	v_lshl_add_u64 v[18:19], v[16:17], 2, s[34:35]
	v_lshl_add_u64 v[16:17], v[16:17], 1, s[62:63]
	global_load_dword v82, v[2:3], off
	global_load_ushort v122, v[0:1], off
	global_load_dword v83, v[6:7], off
	global_load_ushort v120, v[4:5], off
	global_load_dword v76, v[10:11], off
	global_load_ushort v119, v[8:9], off
	global_load_dword v77, v[18:19], off
	global_load_ushort v118, v[16:17], off
	v_add_u32_e32 v0, s0, v105
	v_ashrrev_i32_e32 v1, 31, v0
	v_readlane_b32 s0, v254, 4
	v_lshlrev_b64 v[0:1], 10, v[0:1]
	v_readlane_b32 s1, v254, 5
	v_lshlrev_b32_e32 v6, 2, v93
	v_or_b32_e32 v7, v6, v13
	v_lshl_add_u64 v[0:1], s[0:1], 0, v[0:1]
	v_lshl_add_u64 v[0:1], v[0:1], 0, v[224:225]
	global_load_dwordx4 v[0:3], v[0:1], off
	v_lshlrev_b32_e32 v113, 2, v7
	v_and_b32_e32 v7, -16, v15
	v_lshl_add_u64 v[80:81], s[0:1], 0, v[224:225]
	v_or_b32_e32 v8, v7, v12
	s_movk_i32 s0, 0x110
	v_or_b32_e32 v10, 2, v6
	v_lshlrev_b32_e32 v4, 5, v14
	v_mul_lo_u32 v112, v8, s0
	v_cmp_gt_i32_e64 s[18:19], v10, v8
	v_or_b32_e32 v10, 3, v6
	s_movk_i32 s0, 0x60
	v_or_b32_e32 v7, v6, v7
	v_cmp_gt_i32_e64 s[20:21], v10, v8
	v_or_b32_e32 v10, 16, v6
	v_and_or_b32 v68, v4, s0, v12
	v_readlane_b32 s0, v251, 17
	v_cmp_gt_i32_e64 s[6:7], v10, v8
	v_or_b32_e32 v10, 17, v6
	v_mul_lo_u32 v89, v7, s0
	v_or_b32_e32 v5, v4, v69
	v_cmp_gt_i32_e64 s[16:17], v6, v8
	v_cmp_lt_i32_e64 s[14:15], v6, v8
	v_cmp_gt_i32_e64 s[8:9], v10, v8
	v_or_b32_e32 v10, 18, v6
	v_or_b32_e32 v6, 19, v6
	v_readlane_b32 s4, v254, 11
	v_add_u32_e32 v88, s0, v89
	v_add_u32_e32 v5, 0x12c00, v5
	v_or_b32_e32 v9, 0x12c00, v92
	v_mul_u32_u24_e32 v100, 0x110, v12
	v_cmp_gt_i32_e64 s[12:13], v6, v8
	v_mul_u32_u24_e32 v6, 0x110, v68
	v_lshlrev_b32_e32 v224, 2, v68
	v_readlane_b32 s5, v254, 12
	v_add_u32_e32 v87, s0, v88
	v_mov_b32_e32 v4, 0
	v_mul_u32_u24_e32 v116, 0x880, v93
	v_mul_u32_u24_e32 v115, 0x110, v32
	v_lshlrev_b32_e32 v108, 2, v31
	v_mul_u32_u24_e32 v117, 0x50, v12
	v_cmp_gt_i32_e64 s[10:11], v10, v8
	v_mul_u32_u24_e32 v90, 0x50, v68
	v_lshl_add_u64 v[70:71], s[4:5], 0, v[224:225]
	v_add_u32_e32 v86, s0, v87
	s_mov_b32 s50, 0
	s_movk_i32 s51, 0x8ff
	v_add_u32_e32 v91, v5, v100
	v_add_u32_e32 v75, v9, v6
	s_mov_b32 s61, 0
	v_mov_b32_e32 v5, v4
	v_mov_b32_e32 v6, v4
	v_mov_b32_e32 v7, v4
	v_mov_b32_e32 v36, v4
	v_mov_b32_e32 v37, v4
	v_mov_b32_e32 v38, v4
	v_mov_b32_e32 v39, v4
	v_mov_b32_e32 v12, v4
	v_mov_b32_e32 v13, v4
	v_mov_b32_e32 v14, v4
	v_mov_b32_e32 v15, v4
	v_mov_b32_e32 v40, v4
	v_mov_b32_e32 v41, v4
	v_mov_b32_e32 v42, v4
	v_mov_b32_e32 v43, v4
	v_mov_b32_e32 v16, v4
	v_mov_b32_e32 v17, v4
	v_mov_b32_e32 v18, v4
	v_mov_b32_e32 v19, v4
	v_mov_b32_e32 v44, v4
	v_mov_b32_e32 v45, v4
	v_mov_b32_e32 v46, v4
	v_mov_b32_e32 v47, v4
	v_mov_b32_e32 v20, v4
	v_mov_b32_e32 v21, v4
	v_mov_b32_e32 v22, v4
	v_mov_b32_e32 v23, v4
	v_mov_b32_e32 v48, v4
	v_mov_b32_e32 v49, v4
	v_mov_b32_e32 v50, v4
	v_mov_b32_e32 v51, v4
	v_mov_b32_e32 v24, v4
	v_mov_b32_e32 v25, v4
	v_mov_b32_e32 v26, v4
	v_mov_b32_e32 v27, v4
	v_mov_b32_e32 v52, v4
	v_mov_b32_e32 v53, v4
	v_mov_b32_e32 v54, v4
	v_mov_b32_e32 v55, v4
	v_mov_b32_e32 v28, v4
	v_mov_b32_e32 v29, v4
	v_mov_b32_e32 v30, v4
	v_mov_b32_e32 v31, v4
	v_mov_b32_e32 v56, v4
	v_mov_b32_e32 v57, v4
	v_mov_b32_e32 v58, v4
	v_mov_b32_e32 v59, v4
	v_mov_b32_e32 v32, v4
	v_mov_b32_e32 v33, v4
	v_mov_b32_e32 v34, v4
	v_mov_b32_e32 v35, v4
	v_mov_b32_e32 v60, v4
	v_mov_b32_e32 v61, v4
	v_mov_b32_e32 v62, v4
	v_mov_b32_e32 v63, v4
	v_mov_b32_e32 v8, v4
	v_mov_b32_e32 v9, v4
	v_mov_b32_e32 v10, v4
	v_mov_b32_e32 v11, v4
	v_mov_b32_e32 v64, v4
	v_mov_b32_e32 v65, v4
	v_mov_b32_e32 v66, v4
	v_mov_b32_e32 v67, v4
	v_lshlrev_b32_e32 v208, 2, v72
	v_lshl_add_u32 v200, v114, 11, v208
	v_lshl_add_u32 v201, v94, 11, v208
	v_lshl_add_u32 v202, v95, 11, v208
	v_lshl_add_u32 v203, v96, 11, v208
	v_lshl_add_u32 v204, v97, 11, v208
	v_lshl_add_u32 v205, v99, 11, v208
	v_lshl_add_u32 v206, v101, 11, v208
	v_lshl_add_u32 v207, v103, 11, v208

; __device__ __forceinline__ void hgrn_phase(const Params& P, char* shm, int lbid) {
;     ...
;       if (c + 1 < NCH) HG_PRODUCE(c + 1);
;       if (c + 2 < NCH) HG_ISSUE(c + 2);
;       __syncthreads();
;       const char* pb = shm + (c & 1) * PB;
;       {
;         const bf16x8 a = *(const bf16x8*)(pb + PB_KT + (16 * w + fr) * TSTR + quad * 16);
;         const float4 gl = *(const float4*)(pb + PB_GL + (16 * w + quad * 4) * 4);
; #pragma unroll
;         for (int vt = 0; vt < 8; ++vt) {
;           const bf16x8 bv = *(const bf16x8*)(pb + PB_VT + (vt * 16 + fr) * TSTR + quad * 16);
;           f32x4 t = __builtin_amdgcn_mfma_f32_16x16x32_bf16(a, bv, Sacc[vt], 0, 0, 0);
;           t[0] *= gl.x; t[1] *= gl.y; t[2] *= gl.z; t[3] *= gl.w;
;           Sacc[vt] = t;
;         }
;       }
;       {
;         const int tt = w >> 2, vt0 = (w & 3) * 2;
;         bf16x8 qf[4];
; #pragma unroll
;         for (int ks = 0; ks < 4; ++ks) qf[ks] = *(const bf16x8*)(pb + PB_Q + (tt * 16 + fr) * QSTR + (ks * 32 + quad * 8) * 2);
;         f32x4 AT[2];
; #pragma unroll
;         for (int st = 0; st < 2; ++st) {
;           f32x4 acc = f32x4{0.f, 0.f, 0.f, 0.f};
; #pragma unroll
;           for (int ks = 0; ks < 4; ++ks) {
;             const bf16x8 kf = *(const bf16x8*)(pb + PB_K + (st * 16 + fr) * QSTR + (ks * 32 + quad * 8) * 2);
;             acc = __builtin_amdgcn_mfma_f32_16x16x32_bf16(kf, qf[ks], acc, 0, 0, 0);
;           }
;           const int tpos = tt * 16 + fr;
; #pragma unroll
;           for (int jj = 0; jj < 4; ++jj)
;             if (st * 16 + quad * 4 + jj > tpos) acc[jj] = 0.0f;
;           AT[st] = acc;
;         }
.LBB0_922:
	s_lshl_b32 s98, s5, 11
	v_add_u32_e32 v0, s98, v200
	v_lshrrev_b32_e32 v1, 1, v0
	global_load_dword v84, v0, s[34:35]
	global_load_ushort v24, v1, s[62:63]
	v_add_u32_e32 v0, s98, v201
	v_lshrrev_b32_e32 v1, 1, v0
	global_load_dword v85, v0, s[34:35]
	global_load_ushort v25, v1, s[62:63]
	v_add_u32_e32 v0, s98, v202
	v_lshrrev_b32_e32 v1, 1, v0
	global_load_dword v78, v0, s[34:35]
	global_load_ushort v26, v1, s[62:63]
	v_add_u32_e32 v0, s98, v203
	v_lshrrev_b32_e32 v1, 1, v0
	global_load_dword v79, v0, s[34:35]
	global_load_ushort v27, v1, s[62:63]
	v_add_u32_e32 v0, s98, v204
	v_lshrrev_b32_e32 v1, 1, v0
	global_load_dword v82, v0, s[34:35]
	global_load_ushort v118, v1, s[62:63]
	v_add_u32_e32 v0, s98, v205
	v_lshrrev_b32_e32 v1, 1, v0
	global_load_dword v83, v0, s[34:35]
	global_load_ushort v119, v1, s[62:63]
	v_add_u32_e32 v0, s98, v206
	v_lshrrev_b32_e32 v1, 1, v0
	global_load_dword v76, v0, s[34:35]
	global_load_ushort v127, v1, s[62:63]
	v_add_u32_e32 v0, s98, v207
	v_lshrrev_b32_e32 v1, 1, v0
	global_load_dword v77, v0, s[34:35]
	global_load_ushort v128, v1, s[62:63]
	v_add_u32_e32 v0, s5, v105
	v_ashrrev_i32_e32 v1, 31, v0
	v_lshlrev_b64 v[0:1], 10, v[0:1]
	v_lshl_add_u64 v[0:1], v[80:81], 0, v[0:1]
	global_load_dwordx4 v[0:3], v[0:1], off
	s_bitcmp1_b32 s61, 0
	s_cselect_b32 s74, 0x9600, 0
	v_add_u32_e32 v4, s74, v74
	v_add_u32_e32 v126, v4, v92
	s_waitcnt lgkmcnt(0)
	s_barrier
	ds_read_b128 v[120:123], v126 offset:17408
	v_or_b32_e32 v124, s74, v92
	v_add_u32_e32 v125, v124, v117
	ds_read_b128 v[4:7], v125 offset:27648
	ds_read_b128 v[8:11], v125 offset:28928
	s_waitcnt lgkmcnt(0)
	v_mfma_f32_16x16x32_bf16 v[12:15], v[120:123], v[8:11], v[40:43]
	ds_read_b128 v[8:11], v125 offset:30208
	ds_read_b128 v[28:31], v125 offset:34048
	ds_read_b128 v[32:35], v125 offset:35328
	s_waitcnt lgkmcnt(2)
	v_mfma_f32_16x16x32_bf16 v[16:19], v[120:123], v[8:11], v[44:47]
	ds_read_b128 v[8:11], v125 offset:31488
	s_cmp_gt_u32 s61, 7
	s_mov_b64 s[0:1], -1
	v_mfma_f32_16x16x32_bf16 v[4:7], v[120:123], v[4:7], v[36:39]
	s_waitcnt lgkmcnt(0)
	v_mfma_f32_16x16x32_bf16 v[20:23], v[120:123], v[8:11], v[48:51]
	ds_read_b128 v[8:11], v125 offset:32768
	ds_read_b128 v[36:39], v125 offset:36608
	v_add_u32_e32 v125, v124, v100
	ds_read_b128 v[40:43], v125 offset:8704
	v_add_u32_e32 v124, v124, v112
	ds_read_b128 v[48:51], v124
	v_mfma_f32_16x16x32_bf16 v[28:31], v[120:123], v[28:31], v[56:59]
	s_waitcnt lgkmcnt(2)
	v_mfma_f32_16x16x32_bf16 v[56:59], v[120:123], v[36:39], v[64:67]
	ds_read_b128 v[36:39], v125 offset:8768
	ds_read_b128 v[44:47], v124 offset:64
	v_mfma_f32_16x16x32_bf16 v[8:11], v[120:123], v[8:11], v[52:55]
	s_waitcnt lgkmcnt(2)
	v_mfma_f32_16x16x32_bf16 v[52:55], v[40:43], v[48:51], 0
	v_mfma_f32_16x16x32_bf16 v[32:35], v[120:123], v[32:35], v[60:63]
	s_nop 2
	ds_read_b128 v[60:63], v125 offset:8832
	ds_read_b128 v[40:43], v124 offset:128
	ds_read_b128 v[64:67], v125 offset:13120
	ds_read_b128 v[120:123], v125 offset:13248
	s_waitcnt lgkmcnt(4)
	v_mfma_f32_16x16x32_bf16 v[36:39], v[36:39], v[44:47], v[52:55]
	s_nop 2
	ds_read_b128 v[52:55], v125 offset:8896
	s_waitcnt lgkmcnt(3)
	v_mfma_f32_16x16x32_bf16 v[60:63], v[60:63], v[40:43], v[36:39]
	s_nop 2
	ds_read_b128 v[36:39], v124 offset:192
	s_waitcnt lgkmcnt(0)
	v_mfma_f32_16x16x32_bf16 v[52:55], v[52:55], v[36:39], v[60:63]
	s_nop 2
	ds_read_b128 v[60:63], v125 offset:13056
	s_waitcnt lgkmcnt(0)
	v_mfma_f32_16x16x32_bf16 v[60:63], v[60:63], v[48:51], 0
	v_mfma_f32_16x16x32_bf16 v[60:63], v[64:67], v[44:47], v[60:63]
	ds_read_b128 v[64:67], v125 offset:13184
	s_waitcnt lgkmcnt(0)
	v_mfma_f32_16x16x32_bf16 v[60:63], v[64:67], v[40:43], v[60:63]
	v_add_u32_e32 v64, s74, v113
	ds_read_b128 v[64:67], v64 offset:37888
	v_mfma_f32_16x16x32_bf16 v[60:63], v[120:123], v[36:39], v[60:63]
	s_cbranch_scc0 .LBB0_924
	v_readlane_b32 s0, v251, 15
	s_add_i32 s5, s50, 0xffffff00
	v_readlane_b32 s1, v251, 16
	s_and_b64 s[0:1], s[0:1], exec
	s_cselect_b32 s0, s5, s51
	v_readlane_b32 s1, v254, 36
	s_add_i32 s5, s0, s1
	s_mov_b64 s[0:1], 0

; __device__ __forceinline__ void hgrn_phase(const Params& P, char* shm, int lbid) {
;     ...
;       {
;         const int tt = w >> 2, vt0 = (w & 3) * 2;
;         bf16x8 qf[4];
; #pragma unroll
;         for (int ks = 0; ks < 4; ++ks) qf[ks] = *(const bf16x8*)(pb + PB_Q + (tt * 16 + fr) * QSTR + (ks * 32 + quad * 8) * 2);
;         f32x4 AT[2];
; #pragma unroll
;         for (int st = 0; st < 2; ++st) {
;           f32x4 acc = f32x4{0.f, 0.f, 0.f, 0.f};
; #pragma unroll
;           for (int ks = 0; ks < 4; ++ks) {
;             const bf16x8 kf = *(const bf16x8*)(pb + PB_K + (st * 16 + fr) * QSTR + (ks * 32 + quad * 8) * 2);
;             acc = __builtin_amdgcn_mfma_f32_16x16x32_bf16(kf, qf[ks], acc, 0, 0, 0);
;           }
;           const int tpos = tt * 16 + fr;
; #pragma unroll
;           for (int jj = 0; jj < 4; ++jj)
;             if (st * 16 + quad * 4 + jj > tpos) acc[jj] = 0.0f;
;           AT[st] = acc;
;         }
;         u32x4 ap;
;         ap.x = pack2(AT[0][0], AT[0][1]); ap.y = pack2(AT[0][2], AT[0][3]);
;         ap.z = pack2(AT[1][0], AT[1][1]); ap.w = pack2(AT[1][2], AT[1][3]);
;         const int r0 = HG_R0(c);
; #pragma unroll
;         for (int e = 0; e < 2; ++e) {
;           const int vt = vt0 + e;
;           f32x4 O = f32x4{0.f, 0.f, 0.f, 0.f};
; #pragma unroll
;           for (int ks = 0; ks < 4; ++ks) {
;             const bf16x8 sf = *(const bf16x8*)(sb + (vt * 16 + fr) * QSTR + (ks * 32 + quad * 8) * 2);
;             O = __builtin_amdgcn_mfma_f32_16x16x32_bf16(qf[ks], sf, O, 0, 0, 0);
;           }
;           const char* vp = pb + PB_VT + (vt * 16 + fr) * TSTR + quad * 8;
;           const u32x2 lo = *(const u32x2*)vp, hi = *(const u32x2*)(vp + 32);
;           u32x4 bp; bp.x = lo.x; bp.y = lo.y; bp.z = hi.x; bp.w = hi.y;
;           O = __builtin_amdgcn_mfma_f32_16x16x32_bf16(__builtin_bit_cast(bf16x8, ap), __builtin_bit_cast(bf16x8, bp), O, 0, 0, 0);
; #pragma unroll
;           for (int jj = 0; jj < 4; ++jj)
;             Oo[(size_t)(r0 + sgn * (tt * 16 + quad * 4 + jj)) * 512 + h * 128 + vt * 16 + fr] = O[jj];
;         }
;       }
;       __syncthreads();
.LBB0_926:
	s_waitcnt vmcnt(15)
	v_and_b32_e32 v125, 0xffff, v24
	s_waitcnt vmcnt(13)
	v_and_b32_e32 v124, 0xffff, v25
	s_waitcnt lgkmcnt(0)
	v_pk_mul_f32 v[24:25], v[64:65], v[8:9]
	v_pk_mul_f32 v[8:9], v[64:65], v[56:57]
	v_mov_b32_e32 v56, s75
	v_cndmask_b32_e64 v56, v52, v56, s[16:17]
	v_cndmask_b32_e64 v56, v56, v52, s[14:15]
	v_mov_b32_e32 v52, s75
	s_waitcnt vmcnt(11)
	v_and_b32_e32 v123, 0xffff, v26
	s_waitcnt vmcnt(9)
	v_and_b32_e32 v121, 0xffff, v27
	v_pk_mul_f32 v[26:27], v[66:67], v[10:11]
	v_pk_mul_f32 v[10:11], v[66:67], v[58:59]
	v_cndmask_b32_e64 v53, 0, v53, s[14:15]
	v_cndmask_b32_e64 v54, v54, 0, s[18:19]
	v_cndmask_b32_e64 v55, v55, 0, s[20:21]
	v_cndmask_b32_e64 v57, v60, v52, s[6:7]
	v_cndmask_b32_e64 v58, v61, 0, s[8:9]
	v_cndmask_b32_e64 v59, v62, 0, s[10:11]
	v_cndmask_b32_e64 v60, v63, 0, s[12:13]
	v_cvt_pk_bf16_f32 v52, v56, v53
	v_cvt_pk_bf16_f32 v53, v54, v55
	v_cvt_pk_bf16_f32 v54, v57, v58
	v_cvt_pk_bf16_f32 v55, v59, v60
	ds_read_b128 v[56:59], v75
	ds_read_b128 v[60:63], v75 offset:64
	s_waitcnt lgkmcnt(1)
	v_mfma_f32_16x16x32_bf16 v[56:59], v[48:51], v[56:59], 0
	s_waitcnt vmcnt(5)
	v_and_b32_e32 v120, 0xffff, v119
	s_waitcnt vmcnt(3)
	v_and_b32_e32 v119, 0xffff, v127
	v_add3_u32 v127, s74, v69, v90
	s_waitcnt lgkmcnt(0)
	v_mfma_f32_16x16x32_bf16 v[56:59], v[44:47], v[60:63], v[56:59]
	ds_read_b128 v[60:63], v75 offset:128
	v_pk_mul_f32 v[4:5], v[64:65], v[4:5]
	v_pk_mul_f32 v[12:13], v[64:65], v[12:13]
	s_waitcnt lgkmcnt(0)
	v_mfma_f32_16x16x32_bf16 v[56:59], v[40:43], v[60:63], v[56:59]
	ds_read_b128 v[60:63], v75 offset:192
	v_pk_mul_f32 v[16:17], v[64:65], v[16:17]
	v_pk_mul_f32 v[20:21], v[64:65], v[20:21]
	s_waitcnt lgkmcnt(0)
	v_mfma_f32_16x16x32_bf16 v[56:59], v[36:39], v[60:63], v[56:59]
	v_add_u32_e32 v60, 0x6800, v127
	ds_read2_b64 v[60:63], v60 offset0:128 offset1:132
	v_pk_mul_f32 v[28:29], v[64:65], v[28:29]
	s_waitcnt lgkmcnt(0)
	v_mfma_f32_16x16x32_bf16 v[56:59], v[52:55], v[60:63], v[56:59]
	v_add_u32_e32 v60, s5, v89
	v_ashrrev_i32_e32 v61, 31, v60
	v_add_u32_e32 v62, s5, v88
	v_lshlrev_b64 v[60:61], 11, v[60:61]
	v_ashrrev_i32_e32 v63, 31, v62
	v_lshl_add_u64 v[60:61], v[70:71], 0, v[60:61]
	v_lshlrev_b64 v[62:63], 11, v[62:63]
	s_nop 0
	global_store_dword v[60:61], v56, off
	v_lshl_add_u64 v[62:63], v[70:71], 0, v[62:63]
	v_add_u32_e32 v56, s5, v87
	global_store_dword v[62:63], v57, off
	v_ashrrev_i32_e32 v57, 31, v56
	v_lshlrev_b64 v[56:57], 11, v[56:57]
	v_pk_mul_f32 v[32:33], v[64:65], v[32:33]
	v_lshl_add_u64 v[64:65], v[70:71], 0, v[56:57]
	v_add_u32_e32 v56, s5, v86
	v_ashrrev_i32_e32 v57, 31, v56
	v_lshlrev_b64 v[56:57], 11, v[56:57]
	v_pk_mul_f32 v[6:7], v[66:67], v[6:7]
	v_pk_mul_f32 v[14:15], v[66:67], v[14:15]
	v_pk_mul_f32 v[18:19], v[66:67], v[18:19]
	v_pk_mul_f32 v[22:23], v[66:67], v[22:23]
	v_pk_mul_f32 v[30:31], v[66:67], v[30:31]
	v_pk_mul_f32 v[34:35], v[66:67], v[34:35]
	v_lshl_add_u64 v[66:67], v[70:71], 0, v[56:57]
	global_store_dword v[64:65], v58, off
	global_store_dword v[66:67], v59, off
	ds_read_b128 v[56:59], v75 offset:4352
	s_waitcnt lgkmcnt(0)
	v_mfma_f32_16x16x32_bf16 v[48:51], v[48:51], v[56:59], 0
	ds_read_b128 v[56:59], v75 offset:4416
	s_add_i32 s50, s50, 32
	s_sub_i32 s51, s51, 32
	s_waitcnt lgkmcnt(0)
	v_mfma_f32_16x16x32_bf16 v[44:47], v[44:47], v[56:59], v[48:51]
	v_and_b32_e32 v122, 0xffff, v118
	s_nop 1
	ds_read_b128 v[48:51], v75 offset:4480
	s_waitcnt vmcnt(5)
	v_and_b32_e32 v118, 0xffff, v128
	s_waitcnt lgkmcnt(0)
	v_mfma_f32_16x16x32_bf16 v[40:43], v[40:43], v[48:51], v[44:47]
	s_nop 2
	ds_read_b128 v[44:47], v75 offset:4544
	s_cmpk_eq_i32 s50, 0x8c0
	s_waitcnt lgkmcnt(0)
	v_mfma_f32_16x16x32_bf16 v[36:39], v[36:39], v[44:47], v[40:43]
	s_nop 2
	v_add_u32_e32 v40, 0x7000, v127
	ds_read2_b64 v[40:43], v40 offset0:32 offset1:36
	s_waitcnt lgkmcnt(0)
	v_mfma_f32_16x16x32_bf16 v[36:39], v[52:55], v[40:43], v[36:39]
	s_nop 7
	global_store_dword v[60:61], v36, off offset:64
	global_store_dword v[62:63], v37, off offset:64
	global_store_dword v[64:65], v38, off offset:64
	global_store_dword v[66:67], v39, off offset:64
	s_barrier
	s_cbranch_scc1 .LBB0_928
	s_mov_b32 s61, s4
	v_mov_b64_e32 v[36:37], v[4:5]
	v_mov_b64_e32 v[38:39], v[6:7]
	v_mov_b64_e32 v[40:41], v[12:13]
	v_mov_b64_e32 v[42:43], v[14:15]
	v_mov_b64_e32 v[44:45], v[16:17]
	v_mov_b64_e32 v[46:47], v[18:19]
	v_mov_b64_e32 v[48:49], v[20:21]
	v_mov_b64_e32 v[50:51], v[22:23]
	v_mov_b64_e32 v[52:53], v[24:25]
	v_mov_b64_e32 v[54:55], v[26:27]
	v_mov_b64_e32 v[56:57], v[28:29]
	v_mov_b64_e32 v[58:59], v[30:31]
	v_mov_b64_e32 v[60:61], v[32:33]
	v_mov_b64_e32 v[62:63], v[34:35]
	v_mov_b64_e32 v[64:65], v[8:9]
	v_mov_b64_e32 v[66:67], v[10:11]
	s_branch .LBB0_908

; __global__ void __launch_bounds__(NTHR) fwd_megakernel(Params P) {
;   __shared__ __attribute__((aligned(1024))) char shm[131072];
	.amdhsa_kernel _Z14fwd_megakernel6Params
		.amdhsa_group_segment_fixed_size 131088
		.amdhsa_private_segment_fixed_size 0
		.amdhsa_kernarg_size 464
		.amdhsa_user_sgpr_count 2
		.amdhsa_user_sgpr_dispatch_ptr 0
		.amdhsa_user_sgpr_queue_ptr 0
		.amdhsa_user_sgpr_kernarg_segment_ptr 1
		.amdhsa_user_sgpr_dispatch_id 0
		.amdhsa_user_sgpr_kernarg_preload_length 0
		.amdhsa_user_sgpr_kernarg_preload_offset 0
		.amdhsa_user_sgpr_private_segment_size 0
		.amdhsa_uses_dynamic_stack 0
		.amdhsa_enable_private_segment 0
		.amdhsa_system_sgpr_workgroup_id_x 1
		.amdhsa_system_sgpr_workgroup_id_y 0
		.amdhsa_system_sgpr_workgroup_id_z 0
		.amdhsa_system_sgpr_workgroup_info 0
		.amdhsa_system_vgpr_workitem_id 2
		.amdhsa_next_free_vgpr 256
		.amdhsa_next_free_sgpr 102
		.amdhsa_accum_offset 256
		.amdhsa_reserve_vcc 1
		.amdhsa_float_round_mode_32 0
		.amdhsa_float_round_mode_16_64 0
		.amdhsa_float_denorm_mode_32 3
		.amdhsa_float_denorm_mode_16_64 3
		.amdhsa_dx10_clamp 1
		.amdhsa_ieee_mode 1
		.amdhsa_fp16_overflow 0
		.amdhsa_tg_split 0
		.amdhsa_exception_fp_ieee_invalid_op 0
		.amdhsa_exception_fp_denorm_src 0
		.amdhsa_exception_fp_ieee_div_zero 0
		.amdhsa_exception_fp_ieee_overflow 0
		.amdhsa_exception_fp_ieee_underflow 0
		.amdhsa_exception_fp_ieee_inexact 0
		.amdhsa_exception_int_div_zero 0
	.end_amdhsa_kernel

; __global__ void __launch_bounds__(NTHR) fwd_megakernel(Params P) {
;   __shared__ __attribute__((aligned(1024))) char shm[131072];
amdhsa.kernels:
  - .agpr_count:     0
    .args:
      - .offset:         0
        .size:           208
        .value_kind:     by_value
      - .offset:         208
        .size:           4
        .value_kind:     hidden_block_count_x
      - .offset:         212
        .size:           4
        .value_kind:     hidden_block_count_y
      - .offset:         216
        .size:           4
        .value_kind:     hidden_block_count_z
      - .offset:         220
        .size:           2
        .value_kind:     hidden_group_size_x
      - .offset:         222
        .size:           2
        .value_kind:     hidden_group_size_y
      - .offset:         224
        .size:           2
        .value_kind:     hidden_group_size_z
      - .offset:         226
        .size:           2
        .value_kind:     hidden_remainder_x
      - .offset:         228
        .size:           2
        .value_kind:     hidden_remainder_y
      - .offset:         230
        .size:           2
        .value_kind:     hidden_remainder_z
      - .offset:         248
        .size:           8
        .value_kind:     hidden_global_offset_x
      - .offset:         256
        .size:           8
        .value_kind:     hidden_global_offset_y
      - .offset:         264
        .size:           8
        .value_kind:     hidden_global_offset_z
      - .offset:         272
        .size:           2
        .value_kind:     hidden_grid_dims
      - .offset:         296
        .size:           8
        .value_kind:     hidden_multigrid_sync_arg
    .group_segment_fixed_size: 131088
    .kernarg_segment_align: 8
    .kernarg_segment_size: 464
    .language:       OpenCL C
    .language_version:
      - 2
      - 0
    .max_flat_workgroup_size: 512
    .name:           _Z14fwd_megakernel6Params
    .private_segment_fixed_size: 0
    .sgpr_count:     108
    .sgpr_spill_count: 378
    .symbol:         _Z14fwd_megakernel6Params.kd
    .uniform_work_group_size: 1
    .uses_dynamic_stack: false
    .vgpr_count:     256
    .vgpr_spill_count: 0
    .wavefront_size: 64
